# attention wave mapping: SIMD partner waves take different query halves
# speedup vs baseline: 1.0056x; 1.0056x over previous
.LBB0_396:
	s_waitcnt vmcnt(0)
	s_barrier
	v_readlane_b32 s3, v254, 20
	v_readlane_b32 s2, v254, 4
	s_add_i32 s0, s3, 1
	s_lshr_b32 s2, s2, 3
	s_lshl_b32 s3, s3, 5
	v_writelane_b32 v254, s0, 20
	s_add_i32 s3, s3, s2
	v_mov_b32_e32 v0, s3
	s_movk_i32 s0, 0x7f
	s_waitcnt lgkmcnt(0)
	v_cmp_lt_i32_e32 vcc, s0, v0
	s_mov_b64 s[0:1], -1
	s_cbranch_vccnz .LBB0_395
	v_mov_b32_e32 v96, v193
	s_add_i32 s0, s3, s69
	s_bfe_u32 s2, s3, 0x10005
	v_readfirstlane_b32 s1, v96
	s_ashr_i32 s4, s0, 6
	s_and_b32 s72, s3, 31
	s_bfe_u32 s0, s1, 0x20006
	s_lshl_b32 s3, s2, 2
	s_add_i32 s0, s0, s3
	v_bfe_u32 v97, v96, 5, 1
	s_bfe_u32 s7, s1, 0x10008
	s_lshl_b32 s36, s0, 6
	s_lshl_b32 s1, s72, 7
	s_lshl_b32 s6, s7, 6
	s_ashr_i32 s37, s36, 31
	v_lshlrev_b32_e32 v40, 3, v97
	s_or_b32 s70, s6, s1
	s_lshl_b32 s71, s4, 12
	s_lshl_b64 s[36:37], s[36:37], 1
	v_cvt_f32_ubyte0_e32 v9, v40
	v_and_b32_e32 v222, 31, v96
	s_add_u32 s52, s28, s36
	v_cmp_lt_i32_e32 vcc, v208, v209
	v_mul_f32_e32 v10, 0xbf549a78, v9
	v_or_b32_e32 v80, s70, v222
	s_addc_u32 s53, s29, s37
	v_lshlrev_b32_e32 v198, 4, v97
	v_cndmask_b32_e32 v0, v207, v208, vcc
	v_cmp_gt_f32_e32 vcc, s30, v10
	v_lshl_add_u64 v[56:57], s[52:53], 0, v[198:199]
	v_lshlrev_b32_e32 v221, 2, v0
	v_or_b32_e32 v0, s71, v80
	v_cndmask_b32_e32 v10, 0, v213, vcc
	v_mad_i64_i32 v[0:1], s[52:53], v0, s25, v[56:57]
	v_and_b32_e32 v8, 32, v96
	v_fmac_f32_e32 v10, 0xbf549a78, v9
	s_lshl_b32 s98, s4, 8
	s_add_i32 s98, s98, 0x10000
	v_lshrrev_b32_e32 v238, 2, v193
	v_add_u32_e32 v238, s98, v238
	v_mov_b64_e32 v[240:241], s[28:29]
	v_mad_u64_u32 v[240:241], s[100:101], v238, s25, v[240:241]
	s_lshl_b32 s98, s2, 7
	s_mov_b32 s99, 0
	v_lshl_add_u64 v[240:241], v[240:241], 0, s[98:99]
	v_bfe_u32 v242, v193, 1, 1
	v_mov_b32_e32 v243, 0
	v_lshlrev_b32_e32 v242, 6, v242
	v_lshl_add_u64 v[244:245], v[240:241], 0, v[242:243]
	v_and_b32_e32 v242, 1, v193
	v_lshlrev_b32_e32 v242, 4, v242
	v_lshl_add_u64 v[244:245], v[244:245], 0, v[242:243]
	v_and_b32_e32 v242, 3, v193
	v_lshlrev_b32_e32 v242, 5, v242
	v_lshl_add_u64 v[246:247], v[240:241], 0, v[242:243]
	global_load_dwordx4 v[176:179], v[244:245], off offset:1024
	global_load_dwordx4 v[180:183], v[244:245], off offset:1056
	global_load_dwordx4 v[184:187], v[246:247], off offset:1296
	global_load_dwordx4 v[188:191], v[246:247], off offset:1280
	global_load_dwordx4 v[24:27], v[0:1], off
	global_load_dwordx4 v[28:31], v[0:1], off offset:32
	global_load_dwordx4 v[88:91], v[0:1], off offset:64
	global_load_dwordx4 v[92:95], v[0:1], off offset:96
	global_load_dwordx4 v[16:19], v8, s[14:15]
	global_load_dwordx4 v[20:23], v8, s[14:15] offset:16
	global_load_dwordx4 v[4:7], v8, s[14:15] offset:64
	s_nop 0
	global_load_dwordx4 v[0:3], v8, s[14:15] offset:80
	global_load_dwordx4 v[100:103], v8, s[14:15] offset:128
	global_load_dwordx4 v[52:55], v8, s[14:15] offset:144
	v_exp_f32_e32 v32, v10
	global_load_dwordx4 v[12:15], v8, s[14:15] offset:192
	s_nop 0
	global_load_dwordx4 v[8:11], v8, s[14:15] offset:208
	v_cndmask_b32_e32 v33, 0, v214, vcc
	s_lshr_b32 s1, s70, 6
	v_ldexp_f32 v81, v32, v33
	v_or_b32_e32 v33, 1, v40
	v_cvt_f32_ubyte0_e32 v33, v33
	v_mul_f32_e32 v34, 0xbf549a78, v33
	v_cmp_gt_f32_e32 vcc, s30, v34
	v_cvt_f32_ubyte0_e32 v41, s1
	v_mul_f32_e32 v32, v81, v41
	v_cndmask_b32_e32 v34, 0, v213, vcc
	v_fmac_f32_e32 v34, 0xbf549a78, v33
	v_cvt_f32_ubyte0_e32 v50, v222
	v_mul_f32_e32 v32, 0.15915494, v32
	v_exp_f32_e32 v33, v34
	v_sin_f32_e32 v42, v32
	v_cos_f32_e32 v43, v32
	v_mul_f32_e32 v32, v81, v50
	v_mul_f32_e32 v32, 0.15915494, v32
	v_sin_f32_e32 v62, v32
	v_cos_f32_e32 v63, v32
	v_cndmask_b32_e32 v32, 0, v214, vcc
	v_ldexp_f32 v82, v33, v32
	v_or_b32_e32 v33, 2, v40
	v_cvt_f32_ubyte0_e32 v33, v33
	v_mul_f32_e32 v34, 0xbf549a78, v33
	v_cmp_gt_f32_e32 vcc, s30, v34
	v_mul_f32_e32 v32, v82, v41
	v_mul_f32_e32 v32, 0.15915494, v32
	v_cndmask_b32_e32 v34, 0, v213, vcc
	v_fmac_f32_e32 v34, 0xbf549a78, v33
	v_exp_f32_e32 v33, v34
	v_sin_f32_e32 v45, v32
	v_cos_f32_e32 v44, v32
	v_mul_f32_e32 v32, v82, v50
	v_mul_f32_e32 v32, 0.15915494, v32
	v_sin_f32_e32 v65, v32
	v_cos_f32_e32 v64, v32
	v_cndmask_b32_e32 v32, 0, v214, vcc
	v_ldexp_f32 v83, v33, v32
	v_or_b32_e32 v33, 3, v40
	v_cvt_f32_ubyte0_e32 v33, v33
	v_mul_f32_e32 v34, 0xbf549a78, v33
	v_mul_f32_e32 v32, v83, v41
	v_cmp_gt_f32_e32 vcc, s30, v34
	v_mul_f32_e32 v32, 0.15915494, v32
	v_or_b32_e32 v35, 4, v40
	v_cndmask_b32_e32 v34, 0, v213, vcc
	v_sin_f32_e32 v46, v32
	v_cos_f32_e32 v47, v32
	v_mul_f32_e32 v32, v83, v50
	v_fmac_f32_e32 v34, 0xbf549a78, v33
	v_cvt_f32_ubyte0_e32 v35, v35
	v_mul_f32_e32 v32, 0.15915494, v32
	v_exp_f32_e32 v33, v34
	v_mul_f32_e32 v36, 0xbf549a78, v35
	v_sin_f32_e32 v70, v32
	v_cos_f32_e32 v71, v32
	v_cndmask_b32_e32 v32, 0, v214, vcc
	v_cmp_gt_f32_e32 vcc, s30, v36
	v_ldexp_f32 v84, v33, v32
	v_or_b32_e32 v37, 5, v40
	v_cndmask_b32_e32 v36, 0, v213, vcc
	v_fmac_f32_e32 v36, 0xbf549a78, v35
	v_exp_f32_e32 v35, v36
	v_mul_f32_e32 v34, v84, v50
	v_cvt_f32_ubyte0_e32 v37, v37
	v_mul_f32_e32 v34, 0.15915494, v34
	v_mul_f32_e32 v38, 0xbf549a78, v37
	v_sin_f32_e32 v73, v34
	v_cos_f32_e32 v72, v34
	v_cndmask_b32_e32 v34, 0, v214, vcc
	v_cmp_gt_f32_e32 vcc, s30, v38
	v_ldexp_f32 v85, v35, v34
	v_or_b32_e32 v39, 6, v40
	v_cndmask_b32_e32 v38, 0, v213, vcc
	v_mul_f32_e32 v36, v85, v50
	v_fmac_f32_e32 v38, 0xbf549a78, v37
	v_cvt_f32_ubyte0_e32 v39, v39
	v_mul_f32_e32 v36, 0.15915494, v36
	v_exp_f32_e32 v37, v38
	v_mul_f32_e32 v48, 0xbf549a78, v39
	v_sin_f32_e32 v74, v36
	v_cos_f32_e32 v75, v36
	v_cndmask_b32_e32 v36, 0, v214, vcc
	v_cmp_gt_f32_e32 vcc, s30, v48
	v_ldexp_f32 v86, v37, v36
	v_mul_f32_e32 v38, v86, v50
	v_cndmask_b32_e32 v48, 0, v213, vcc
	v_fmac_f32_e32 v48, 0xbf549a78, v39
	v_exp_f32_e32 v39, v48
	v_mul_f32_e32 v38, 0.15915494, v38
	v_sin_f32_e32 v77, v38
	v_cos_f32_e32 v76, v38
	v_cndmask_b32_e32 v38, 0, v214, vcc
	v_ldexp_f32 v87, v39, v38
	v_mul_f32_e32 v48, v87, v50
	v_or_b32_e32 v40, 7, v40
	v_mul_f32_e32 v48, 0.15915494, v48
	v_cvt_f32_ubyte0_e32 v40, v40
	v_sin_f32_e32 v66, v48
	v_cos_f32_e32 v67, v48
	v_mul_f32_e32 v48, 0xbf549a78, v40
	v_cmp_gt_f32_e32 vcc, s30, v48
	s_waitcnt vmcnt(0)
	v_mov_b32_e32 v49, v10
	v_lshlrev_b32_e32 v60, 16, v91
	v_cndmask_b32_e32 v48, 0, v213, vcc
	v_fmac_f32_e32 v48, 0xbf549a78, v40
	v_exp_f32_e32 v40, v48
	v_cndmask_b32_e32 v10, 0, v214, vcc
	v_and_b32_e32 v104, 0xffff0000, v91
	v_mul_f32_e32 v32, v84, v41
	v_ldexp_f32 v99, v40, v10
	v_mul_f32_e32 v10, v99, v41
	v_mul_f32_e32 v10, 0.15915494, v10
	v_mul_f32_e32 v34, v85, v41
	v_mul_f32_e32 v36, v86, v41
	v_mul_f32_e32 v38, v87, v41
	v_lshlrev_b32_e32 v61, 16, v95
	v_sin_f32_e32 v41, v10
	v_cos_f32_e32 v40, v10
	v_mul_f32_e32 v10, v99, v50
	v_and_b32_e32 v105, 0xffff0000, v95
	v_mov_b32_e32 v50, v104
	v_mov_b32_e32 v51, v60
	v_pk_mul_f32 v[106:107], v[50:51], v[50:51]
	v_mov_b32_e32 v50, v105
	v_mov_b32_e32 v51, v61
	v_pk_mul_f32 v[108:109], v[50:51], v[50:51]
	v_mov_b32_e32 v51, v8
	v_mov_b32_e32 v8, v53
	v_lshlrev_b32_e32 v112, 16, v89
	v_mov_b32_e32 v53, v14
	v_and_b32_e32 v114, 0xffff0000, v89
	v_mov_b32_e32 v14, v103
	v_lshlrev_b32_e32 v103, 16, v92
	v_and_b32_e32 v89, 0xffff0000, v92
	v_lshlrev_b32_e32 v140, 16, v25
	v_and_b32_e32 v144, 0xffff0000, v25
	v_lshlrev_b32_e32 v149, 16, v28
	v_lshlrev_b32_e32 v148, 16, v24
	v_and_b32_e32 v25, 0xffff0000, v28
	v_and_b32_e32 v24, 0xffff0000, v24
	v_mov_b32_e32 v58, v89
	v_mov_b32_e32 v59, v103
	v_lshlrev_b32_e32 v141, 16, v29
	v_and_b32_e32 v145, 0xffff0000, v29
	v_pk_mul_f32 v[150:151], v[148:149], v[148:149]
	v_pk_mul_f32 v[28:29], v[24:25], v[24:25]
	v_lshlrev_b32_e32 v113, 16, v93
	v_and_b32_e32 v115, 0xffff0000, v93
	v_pk_mul_f32 v[92:93], v[58:59], v[58:59]
	v_mov_b32_e32 v58, v22
	v_mov_b32_e32 v22, v20
	v_pk_mul_f32 v[142:143], v[140:141], v[140:141]
	v_add_f32_e32 v20, v150, v28
	v_lshlrev_b32_e32 v137, 16, v30
	v_lshlrev_b32_e32 v136, 16, v26
	v_pk_mul_f32 v[146:147], v[144:145], v[144:145]
	v_add_f32_e32 v20, v142, v20
	v_lshlrev_b32_e32 v128, 16, v27
	v_and_b32_e32 v132, 0xffff0000, v27
	v_pk_mul_f32 v[138:139], v[136:137], v[136:137]
	v_and_b32_e32 v27, 0xffff0000, v30
	v_and_b32_e32 v26, 0xffff0000, v26
	v_add_f32_e32 v20, v146, v20
	v_lshlrev_b32_e32 v129, 16, v31
	v_and_b32_e32 v133, 0xffff0000, v31
	v_pk_mul_f32 v[30:31], v[26:27], v[26:27]
	v_add_f32_e32 v20, v138, v20
	v_pk_mul_f32 v[130:131], v[128:129], v[128:129]
	v_add_f32_e32 v20, v30, v20
	v_pk_mul_f32 v[134:135], v[132:133], v[132:133]
	v_add_f32_e32 v20, v130, v20
	v_add_f32_e32 v20, v134, v20
	v_add_f32_e32 v20, v151, v20
	v_add_f32_e32 v20, v29, v20
	v_add_f32_e32 v20, v143, v20
	v_add_f32_e32 v20, v147, v20
	v_add_f32_e32 v20, v139, v20
	v_add_f32_e32 v20, v31, v20
	v_add_f32_e32 v20, v131, v20
	v_mov_b32_e32 v50, v52
	v_mov_b32_e32 v52, v102
	v_lshlrev_b32_e32 v102, 16, v88
	v_add_f32_e32 v20, v135, v20
	v_and_b32_e32 v88, 0xffff0000, v88
	v_fmac_f32_e32 v20, v102, v102
	v_fmac_f32_e32 v20, v88, v88
	v_fmac_f32_e32 v20, v112, v112
	v_lshlrev_b32_e32 v110, 16, v90
	v_fmac_f32_e32 v20, v114, v114
	v_and_b32_e32 v90, 0xffff0000, v90
	v_fmac_f32_e32 v20, v110, v110
	v_fmac_f32_e32 v20, v90, v90
	v_mul_f32_e32 v10, 0.15915494, v10
	v_lshlrev_b32_e32 v111, 16, v94
	v_and_b32_e32 v91, 0xffff0000, v94
	v_add_f32_e32 v20, v107, v20
	v_mov_b32_e32 v48, v54
	v_sin_f32_e32 v69, v10
	v_cos_f32_e32 v68, v10
	v_mov_b32_e32 v10, v55
	v_mov_b32_e32 v54, v91
	v_mov_b32_e32 v55, v111
	v_add_f32_e32 v20, v106, v20
	v_pk_mul_f32 v[94:95], v[54:55], v[54:55]
	v_mov_b32_e32 v54, v115
	v_mov_b32_e32 v55, v113
	v_add_f32_e32 v20, v93, v20
	v_pk_mul_f32 v[116:117], v[54:55], v[54:55]
	v_add_f32_e32 v20, v92, v20
	v_add_f32_e32 v20, v117, v20
	v_add_f32_e32 v20, v116, v20
	v_add_f32_e32 v20, v95, v20
	v_add_f32_e32 v20, v94, v20
	v_add_f32_e32 v20, v109, v20
	v_add_f32_e32 v20, v108, v20
	ds_bpermute_b32 v30, v221, v20
	v_mov_b32_e32 v29, v6
	v_mov_b32_e32 v28, v18
	v_mov_b32_e32 v31, v4
	v_mov_b32_e32 v54, v100
	s_waitcnt lgkmcnt(0)
	v_add_f32_e32 v6, v20, v30
	v_fmamk_f32 v6, v6, 0x3c800000, v211
	v_mul_f32_e32 v18, 0x4b800000, v6
	v_cmp_gt_f32_e32 vcc, s33, v6
	v_mov_b32_e32 v55, v12
	v_mov_b32_e32 v30, v16
	v_cndmask_b32_e32 v6, v6, v18, vcc
	v_rsq_f32_e32 v18, v6
	v_mov_b32_e32 v12, v101
	v_mov_b32_e32 v59, v2
	v_mov_b32_e32 v2, v23
	v_mul_f32_e32 v4, 0x45800000, v18
	v_cndmask_b32_e32 v16, v18, v4, vcc
	v_pk_mul_f32 v[116:117], v[54:55], v[16:17] op_sel_hi:[1,0]
	v_mov_b32_e32 v23, v0
	v_pk_mul_f32 v[102:103], v[116:117], v[102:103]
	v_pk_mul_f32 v[116:117], v[12:13], v[16:17] op_sel_hi:[1,0]
	v_mov_b32_e32 v0, v21
	v_pk_mul_f32 v[88:89], v[116:117], v[88:89]
	v_pk_mul_f32 v[116:117], v[52:53], v[16:17] op_sel_hi:[1,0]
	v_mov_b32_e32 v4, v17
	v_pk_mul_f32 v[112:113], v[116:117], v[112:113]
	v_pk_mul_f32 v[116:117], v[14:15], v[16:17] op_sel_hi:[1,0]
	v_mov_b32_e32 v6, v19
	v_pk_mul_f32 v[114:115], v[116:117], v[114:115]
	v_pk_mul_f32 v[116:117], v[50:51], v[16:17] op_sel_hi:[1,0]
	v_pk_mul_f32 v[18:19], v[30:31], v[16:17] op_sel_hi:[1,0]
	v_pk_mul_f32 v[110:111], v[116:117], v[110:111]
	v_pk_mul_f32 v[116:117], v[8:9], v[16:17] op_sel_hi:[1,0]
	v_pk_mul_f32 v[20:21], v[4:5], v[16:17] op_sel_hi:[1,0]
	v_pk_mul_f32 v[106:107], v[0:1], v[16:17] op_sel_hi:[1,0]
	v_pk_mul_f32 v[90:91], v[116:117], v[90:91]
	v_pk_mul_f32 v[116:117], v[48:49], v[16:17] op_sel_hi:[1,0]
	v_pk_mul_f32 v[18:19], v[18:19], v[148:149]
	v_pk_mul_f32 v[20:21], v[20:21], v[24:25]
	v_pk_mul_f32 v[24:25], v[28:29], v[16:17] op_sel_hi:[1,0]
	v_pk_mul_f32 v[92:93], v[6:7], v[16:17] op_sel_hi:[1,0]
	v_pk_mul_f32 v[94:95], v[22:23], v[16:17] op_sel_hi:[1,0]
	v_pk_mul_f32 v[26:27], v[106:107], v[26:27]
	v_pk_mul_f32 v[106:107], v[58:59], v[16:17] op_sel_hi:[1,0]
	v_pk_mul_f32 v[108:109], v[2:3], v[16:17] op_sel_hi:[1,0]
	v_pk_mul_f32 v[116:117], v[116:117], v[60:61]
	v_pk_mul_f32 v[16:17], v[10:11], v[16:17] op_sel_hi:[1,0]
	v_mov_b32_e32 v60, v43
	v_mov_b32_e32 v61, v42
	v_pk_mul_f32 v[104:105], v[16:17], v[104:105]
	v_pk_mul_f32 v[16:17], v[60:61], v[18:19]
	v_pk_mul_f32 v[106:107], v[106:107], v[128:129]
	v_sub_f32_e32 v16, v16, v17
	v_mul_f32_e32 v128, 0x3e38aa3b, v16
	v_pk_mul_f32 v[16:17], v[42:43], v[18:19]
	v_mov_b32_e32 v100, v63
	v_mov_b32_e32 v101, v62
	v_add_f32_e32 v16, v16, v17
	v_pk_mul_f32 v[108:109], v[108:109], v[132:133]
	v_mul_f32_e32 v132, 0x3e38aa3b, v16
	v_pk_mul_f32 v[16:17], v[100:101], v[102:103]
	v_pk_mul_f32 v[24:25], v[24:25], v[140:141]
	v_sub_f32_e32 v16, v16, v17
	v_mul_f32_e32 v100, 0x3e38aa3b, v16
	v_pk_mul_f32 v[16:17], v[62:63], v[102:103]
	v_mov_b32_e32 v62, v45
	v_add_f32_e32 v16, v16, v17
	v_mul_f32_e32 v140, 0x3e38aa3b, v16
	v_pk_mul_f32 v[16:17], v[44:45], v[20:21]
	v_mov_b32_e32 v63, v44
	v_sub_f32_e32 v16, v16, v17
	v_mul_f32_e32 v101, 0x3e38aa3b, v16
	v_pk_mul_f32 v[16:17], v[62:63], v[20:21]
	v_mov_b32_e32 v118, v65
	v_add_f32_e32 v16, v16, v17
	v_mul_f32_e32 v102, 0x3e38aa3b, v16
	v_pk_mul_f32 v[16:17], v[64:65], v[88:89]
	v_mov_b32_e32 v119, v64
	v_sub_f32_e32 v16, v16, v17
	v_mul_f32_e32 v103, 0x3e38aa3b, v16
	v_pk_mul_f32 v[16:17], v[118:119], v[88:89]
	v_mov_b32_e32 v64, v47
	v_add_f32_e32 v16, v16, v17
	v_mov_b32_e32 v65, v46
	v_mul_f32_e32 v118, 0x3e38aa3b, v16
	v_pk_mul_f32 v[16:17], v[64:65], v[24:25]
	v_mul_f32_e32 v32, 0.15915494, v32
	v_sub_f32_e32 v16, v16, v17
	v_mul_f32_e32 v119, 0x3e38aa3b, v16
	v_pk_mul_f32 v[16:17], v[46:47], v[24:25]
	v_mov_b32_e32 v120, v71
	v_mov_b32_e32 v121, v70
	v_add_f32_e32 v16, v16, v17
	v_sin_f32_e32 v33, v32
	v_cos_f32_e32 v32, v32
	v_mul_f32_e32 v133, 0x3e38aa3b, v16
	v_pk_mul_f32 v[16:17], v[120:121], v[112:113]
	v_pk_mul_f32 v[92:93], v[92:93], v[144:145]
	v_sub_f32_e32 v16, v16, v17
	v_mul_f32_e32 v120, 0x3e38aa3b, v16
	v_pk_mul_f32 v[16:17], v[70:71], v[112:113]
	v_mul_f32_e32 v35, 0.15915494, v34
	v_add_f32_e32 v16, v16, v17
	v_mul_f32_e32 v70, 0x3e38aa3b, v16
	v_pk_mul_f32 v[16:17], v[32:33], v[92:93]
	v_sin_f32_e32 v34, v35
	v_sub_f32_e32 v16, v16, v17
	v_mul_f32_e32 v71, 0x3e38aa3b, v16
	v_mov_b32_e32 v16, v33
	v_mov_b32_e32 v17, v32
	v_pk_mul_f32 v[18:19], v[16:17], v[92:93]
	v_cos_f32_e32 v35, v35
	v_add_f32_e32 v18, v18, v19
	v_mul_f32_e32 v112, 0x3e38aa3b, v18
	v_pk_mul_f32 v[18:19], v[72:73], v[114:115]
	v_mov_b32_e32 v122, v73
	v_mov_b32_e32 v123, v72
	v_sub_f32_e32 v18, v18, v19
	v_mul_f32_e32 v72, 0x3e38aa3b, v18
	v_pk_mul_f32 v[18:19], v[122:123], v[114:115]
	v_pk_mul_f32 v[94:95], v[94:95], v[136:137]
	v_add_f32_e32 v18, v18, v19
	v_mul_f32_e32 v73, 0x3e38aa3b, v18
	v_mov_b32_e32 v18, v35
	v_mov_b32_e32 v19, v34
	v_pk_mul_f32 v[20:21], v[18:19], v[94:95]
	v_mul_f32_e32 v36, 0.15915494, v36
	v_sub_f32_e32 v20, v20, v21
	v_mul_f32_e32 v113, 0x3e38aa3b, v20
	v_pk_mul_f32 v[20:21], v[34:35], v[94:95]
	v_mov_b32_e32 v124, v75
	v_mov_b32_e32 v125, v74
	v_add_f32_e32 v20, v20, v21
	v_sin_f32_e32 v37, v36
	v_cos_f32_e32 v36, v36
	v_mul_f32_e32 v114, 0x3e38aa3b, v20
	v_pk_mul_f32 v[20:21], v[124:125], v[110:111]
	v_mul_f32_e32 v39, 0.15915494, v38
	v_sub_f32_e32 v20, v20, v21
	v_mul_f32_e32 v115, 0x3e38aa3b, v20
	v_pk_mul_f32 v[20:21], v[74:75], v[110:111]
	v_sin_f32_e32 v38, v39
	v_add_f32_e32 v20, v20, v21
	v_mul_f32_e32 v74, 0x3e38aa3b, v20
	v_pk_mul_f32 v[20:21], v[36:37], v[26:27]
	v_cos_f32_e32 v39, v39
	v_sub_f32_e32 v20, v20, v21
	v_mul_f32_e32 v75, 0x3e38aa3b, v20
	v_mov_b32_e32 v20, v37
	v_mov_b32_e32 v21, v36
	v_pk_mul_f32 v[24:25], v[20:21], v[26:27]
	v_mov_b32_e32 v126, v77
	v_add_f32_e32 v24, v24, v25
	v_mul_f32_e32 v110, 0x3e38aa3b, v24
	v_pk_mul_f32 v[24:25], v[76:77], v[90:91]
	v_mov_b32_e32 v127, v76
	v_sub_f32_e32 v24, v24, v25
	v_mul_f32_e32 v76, 0x3e38aa3b, v24
	v_pk_mul_f32 v[24:25], v[126:127], v[90:91]
	v_mov_b32_e32 v78, v67
	v_add_f32_e32 v24, v24, v25
	v_or_b32_e32 v25, 32, v80
	v_or_b32_e32 v25, s71, v25
	v_mad_i64_i32 v[56:57], s[52:53], v25, s25, v[56:57]
	v_mul_f32_e32 v77, 0x3e38aa3b, v24
	v_mov_b32_e32 v24, v39
	v_mov_b32_e32 v25, v38
	v_pk_mul_f32 v[26:27], v[24:25], v[106:107]
	v_mov_b32_e32 v79, v66
	v_sub_f32_e32 v26, v26, v27
	v_mul_f32_e32 v111, 0x3e38aa3b, v26
	v_pk_mul_f32 v[26:27], v[38:39], v[106:107]
	global_load_dwordx4 v[88:91], v[56:57], off offset:64
	global_load_dwordx4 v[92:95], v[56:57], off offset:96
	v_add_f32_e32 v26, v26, v27
	v_mul_f32_e32 v106, 0x3e38aa3b, v26
	v_pk_mul_f32 v[26:27], v[78:79], v[116:117]
	v_cvt_pk_bf16_f32 v128, v128, v101
	v_cvt_pk_bf16_f32 v132, v132, v102
	v_cvt_pk_bf16_f32 v136, v100, v103
	v_cvt_pk_bf16_f32 v130, v113, v75
	v_cvt_pk_bf16_f32 v142, v74, v77
	s_nop 0
	v_sub_f32_e32 v26, v26, v27
	v_mul_f32_e32 v78, 0x3e38aa3b, v26
	v_pk_mul_f32 v[26:27], v[66:67], v[116:117]
	v_cvt_pk_bf16_f32 v137, v120, v72
	v_cvt_pk_bf16_f32 v141, v70, v73
	v_cvt_pk_bf16_f32 v129, v119, v71
	v_cvt_pk_bf16_f32 v138, v115, v76
	v_cvt_pk_bf16_f32 v134, v114, v110
	s_nop 0
	v_add_f32_e32 v26, v26, v27
	v_mul_f32_e32 v79, 0x3e38aa3b, v26
	v_pk_mul_f32 v[26:27], v[40:41], v[108:109]
	v_cvt_pk_bf16_f32 v140, v140, v118
	v_cvt_pk_bf16_f32 v133, v133, v112
	v_and_b32_e32 v98, 63, v96
	v_sub_f32_e32 v26, v26, v27
	v_mul_f32_e32 v107, 0x3e38aa3b, v26
	v_mov_b32_e32 v26, v41
	v_mov_b32_e32 v27, v40
	v_pk_mul_f32 v[66:67], v[26:27], v[108:109]
	v_cvt_pk_bf16_f32 v131, v111, v107
	s_ashr_i32 s1, s0, 31
	v_add_f32_e32 v66, v66, v67
	v_mul_f32_e32 v108, 0x3e38aa3b, v66
	v_pk_mul_f32 v[66:67], v[68:69], v[104:105]
	v_cvt_pk_bf16_f32 v135, v106, v108
	s_lshl_b64 s[0:1], s[0:1], 2
	v_sub_f32_e32 v66, v66, v67
	v_mul_f32_e32 v109, 0x3e38aa3b, v66
	v_mov_b32_e32 v66, v69
	v_mov_b32_e32 v67, v68
	v_pk_mul_f32 v[66:67], v[66:67], v[104:105]
	global_load_dwordx4 v[100:103], v[56:57], off
	global_load_dwordx4 v[104:107], v[56:57], off offset:32
	v_bitop3_b32 v56, v80, 63, 32 bitop3:0xc8
	v_cvt_f32_ubyte0_e32 v56, v56
	v_mul_f32_e32 v57, v81, v56
	v_mul_f32_e32 v57, 0.15915494, v57
	v_sin_f32_e32 v80, v57
	v_cos_f32_e32 v81, v57
	v_mul_f32_e32 v57, v82, v56
	v_mul_f32_e32 v57, 0.15915494, v57
	v_cvt_pk_bf16_f32 v139, v78, v109
	v_sin_f32_e32 v109, v57
	v_cos_f32_e32 v108, v57
	v_mul_f32_e32 v57, v83, v56
	v_mul_f32_e32 v57, 0.15915494, v57
	v_sin_f32_e32 v74, v57
	v_cos_f32_e32 v75, v57
	v_mul_f32_e32 v57, v84, v56
	v_mul_f32_e32 v57, 0.15915494, v57
	v_sin_f32_e32 v73, v57
	v_cos_f32_e32 v72, v57
	v_mul_f32_e32 v57, v85, v56
	v_mul_f32_e32 v57, 0.15915494, v57
	v_sin_f32_e32 v70, v57
	v_cos_f32_e32 v71, v57
	v_mul_f32_e32 v57, v86, v56
	v_mul_f32_e32 v57, 0.15915494, v57
	v_sin_f32_e32 v69, v57
	v_cos_f32_e32 v68, v57
	v_mul_f32_e32 v57, v87, v56
	v_mul_f32_e32 v56, v99, v56
	v_mov_b32_e32 v122, v81
	v_mov_b32_e32 v123, v80
	v_mov_b32_e32 v124, v109
	v_mov_b32_e32 v125, v108
	v_add_f32_e32 v66, v66, v67
	v_mul_f32_e32 v66, 0x3e38aa3b, v66
	v_cvt_pk_bf16_f32 v143, v79, v66
	v_mov_b32_e32 v78, v75
	v_mov_b32_e32 v79, v74
	s_waitcnt vmcnt(3)
	v_lshlrev_b32_e32 v82, 16, v91
	v_and_b32_e32 v84, 0xffff0000, v91
	s_waitcnt vmcnt(2)
	v_lshlrev_b32_e32 v83, 16, v95
	v_and_b32_e32 v85, 0xffff0000, v95
	v_mov_b32_e32 v76, v84
	v_mov_b32_e32 v77, v82
	v_pk_mul_f32 v[86:87], v[76:77], v[76:77]
	v_mov_b32_e32 v76, v85
	v_mov_b32_e32 v77, v83
	v_lshlrev_b32_e32 v113, 16, v94
	v_and_b32_e32 v91, 0xffff0000, v94
	v_pk_mul_f32 v[110:111], v[76:77], v[76:77]
	v_mov_b32_e32 v76, v91
	v_mov_b32_e32 v77, v113
	v_lshlrev_b32_e32 v115, 16, v93
	v_and_b32_e32 v117, 0xffff0000, v93
	v_pk_mul_f32 v[94:95], v[76:77], v[76:77]
	v_lshlrev_b32_e32 v114, 16, v89
	v_and_b32_e32 v116, 0xffff0000, v89
	v_mov_b32_e32 v76, v117
	v_mov_b32_e32 v77, v115
	v_lshlrev_b32_e32 v121, 16, v92
	v_and_b32_e32 v89, 0xffff0000, v92
	v_pk_mul_f32 v[118:119], v[76:77], v[76:77]
	v_mov_b32_e32 v76, v89
	v_mov_b32_e32 v77, v121
	v_pk_mul_f32 v[92:93], v[76:77], v[76:77]
	v_lshlrev_b32_e32 v120, 16, v88
	v_and_b32_e32 v88, 0xffff0000, v88
	v_lshlrev_b32_e32 v112, 16, v90
	v_and_b32_e32 v90, 0xffff0000, v90
	v_mov_b32_e32 v76, v73
	v_mul_f32_e32 v57, 0.15915494, v57
	v_sin_f32_e32 v66, v57
	v_cos_f32_e32 v67, v57
	s_add_u32 s0, s18, s0
	s_addc_u32 s1, s19, s1
	v_mul_f32_e32 v56, 0.15915494, v56
	v_sin_f32_e32 v57, v56
	v_cos_f32_e32 v56, v56
	s_waitcnt vmcnt(1)
	v_lshlrev_b32_e32 v154, 16, v101
	v_and_b32_e32 v158, 0xffff0000, v101
	s_waitcnt vmcnt(0)
	v_lshlrev_b32_e32 v163, 16, v104
	v_lshlrev_b32_e32 v162, 16, v100
	v_and_b32_e32 v101, 0xffff0000, v104
	v_and_b32_e32 v100, 0xffff0000, v100
	v_lshlrev_b32_e32 v155, 16, v105
	v_and_b32_e32 v159, 0xffff0000, v105
	v_pk_mul_f32 v[164:165], v[162:163], v[162:163]
	v_pk_mul_f32 v[104:105], v[100:101], v[100:101]
	v_pk_mul_f32 v[156:157], v[154:155], v[154:155]
	v_add_f32_e32 v77, v164, v104
	v_lshlrev_b32_e32 v151, 16, v106
	v_lshlrev_b32_e32 v150, 16, v102
	v_pk_mul_f32 v[160:161], v[158:159], v[158:159]
	v_add_f32_e32 v77, v156, v77
	v_lshlrev_b32_e32 v126, 16, v103
	v_and_b32_e32 v146, 0xffff0000, v103
	v_pk_mul_f32 v[152:153], v[150:151], v[150:151]
	v_and_b32_e32 v103, 0xffff0000, v106
	v_and_b32_e32 v102, 0xffff0000, v102
	v_add_f32_e32 v77, v160, v77
	v_lshlrev_b32_e32 v127, 16, v107
	v_and_b32_e32 v147, 0xffff0000, v107
	v_pk_mul_f32 v[106:107], v[102:103], v[102:103]
	v_add_f32_e32 v77, v152, v77
	v_pk_mul_f32 v[144:145], v[126:127], v[126:127]
	v_add_f32_e32 v77, v106, v77
	v_pk_mul_f32 v[148:149], v[146:147], v[146:147]
	v_add_f32_e32 v77, v144, v77
	v_add_f32_e32 v77, v148, v77
	v_add_f32_e32 v77, v165, v77
	v_add_f32_e32 v77, v105, v77
	v_add_f32_e32 v77, v157, v77
	v_add_f32_e32 v77, v161, v77
	v_add_f32_e32 v77, v153, v77
	v_add_f32_e32 v77, v107, v77
	v_add_f32_e32 v77, v145, v77
	v_add_f32_e32 v77, v149, v77
	v_fmac_f32_e32 v77, v120, v120
	v_fmac_f32_e32 v77, v88, v88
	v_fmac_f32_e32 v77, v114, v114
	v_fmac_f32_e32 v77, v116, v116
	v_fmac_f32_e32 v77, v112, v112
	v_fmac_f32_e32 v77, v90, v90
	v_add_f32_e32 v77, v87, v77
	v_add_f32_e32 v77, v86, v77
	v_add_f32_e32 v77, v93, v77
	v_add_f32_e32 v77, v92, v77
	v_add_f32_e32 v77, v119, v77
	v_add_f32_e32 v77, v118, v77
	v_add_f32_e32 v77, v95, v77
	v_add_f32_e32 v77, v94, v77
	v_add_f32_e32 v77, v111, v77
	v_add_f32_e32 v93, v110, v77
	ds_bpermute_b32 v94, v221, v93
	v_mov_b32_e32 v77, v72
	v_mov_b32_e32 v86, v71
	v_mov_b32_e32 v87, v70
	v_mov_b32_e32 v92, v69
	s_waitcnt lgkmcnt(0)
	v_add_f32_e32 v93, v93, v94
	v_fmamk_f32 v93, v93, 0x3c800000, v211
	v_mul_f32_e32 v94, 0x4b800000, v93
	v_cmp_gt_f32_e32 vcc, s33, v93
	v_mov_b32_e32 v95, v66
	s_lshl_b32 s52, s4, 8
	v_cndmask_b32_e32 v93, v93, v94, vcc
	v_rsq_f32_e32 v99, v93
	v_mov_b32_e32 v93, v68
	v_mov_b32_e32 v94, v67
	s_ashr_i32 s53, s52, 31
	v_mul_f32_e32 v104, 0x45800000, v99
	v_cndmask_b32_e32 v104, v99, v104, vcc
	v_pk_mul_f32 v[30:31], v[30:31], v[104:105] op_sel_hi:[1,0]
	v_pk_mul_f32 v[54:55], v[54:55], v[104:105] op_sel_hi:[1,0]
	v_pk_mul_f32 v[30:31], v[30:31], v[162:163]
	v_pk_mul_f32 v[54:55], v[54:55], v[120:121]
	v_pk_mul_f32 v[60:61], v[60:61], v[30:31]
	v_pk_mul_f32 v[30:31], v[42:43], v[30:31]
	v_pk_mul_f32 v[4:5], v[4:5], v[104:105] op_sel_hi:[1,0]
	v_add_f32_e32 v30, v30, v31
	v_mul_f32_e32 v42, 0x3e38aa3b, v30
	v_pk_mul_f32 v[30:31], v[122:123], v[54:55]
	v_pk_mul_f32 v[4:5], v[4:5], v[100:101]
	v_sub_f32_e32 v30, v30, v31
	v_mul_f32_e32 v43, 0x3e38aa3b, v30
	v_pk_mul_f32 v[30:31], v[80:81], v[54:55]
	v_pk_mul_f32 v[12:13], v[12:13], v[104:105] op_sel_hi:[1,0]
	v_add_f32_e32 v30, v30, v31
	v_mul_f32_e32 v54, 0x3e38aa3b, v30
	v_pk_mul_f32 v[30:31], v[44:45], v[4:5]
	v_pk_mul_f32 v[4:5], v[62:63], v[4:5]
	v_pk_mul_f32 v[12:13], v[12:13], v[88:89]
	v_add_f32_e32 v4, v4, v5
	v_sub_f32_e32 v30, v30, v31
	v_mul_f32_e32 v31, 0x3e38aa3b, v4
	v_pk_mul_f32 v[4:5], v[108:109], v[12:13]
	v_pk_mul_f32 v[28:29], v[28:29], v[104:105] op_sel_hi:[1,0]
	v_sub_f32_e32 v4, v4, v5
	v_mul_f32_e32 v44, 0x3e38aa3b, v4
	v_pk_mul_f32 v[4:5], v[124:125], v[12:13]
	v_pk_mul_f32 v[28:29], v[28:29], v[154:155]
	v_add_f32_e32 v4, v4, v5
	v_mul_f32_e32 v12, 0x3e38aa3b, v4
	v_pk_mul_f32 v[4:5], v[64:65], v[28:29]
	v_pk_mul_f32 v[52:53], v[52:53], v[104:105] op_sel_hi:[1,0]
	v_sub_f32_e32 v4, v4, v5
	v_mul_f32_e32 v13, 0x3e38aa3b, v4
	v_pk_mul_f32 v[4:5], v[46:47], v[28:29]
	v_lshlrev_b32_e32 v28, 2, v98
	global_load_dword v29, v28, s[14:15]
	v_pk_mul_f32 v[52:53], v[52:53], v[114:115]
	global_load_dword v28, v28, s[16:17]
	v_add_f32_e32 v4, v4, v5
	v_mul_f32_e32 v45, 0x3e38aa3b, v4
	v_pk_mul_f32 v[4:5], v[78:79], v[52:53]
	v_pk_mul_f32 v[6:7], v[6:7], v[104:105] op_sel_hi:[1,0]
	v_sub_f32_e32 v4, v4, v5
	v_mul_f32_e32 v46, 0x3e38aa3b, v4
	v_pk_mul_f32 v[4:5], v[74:75], v[52:53]
	v_pk_mul_f32 v[6:7], v[6:7], v[158:159]
	v_add_f32_e32 v4, v4, v5
	v_mul_f32_e32 v47, 0x3e38aa3b, v4
	v_pk_mul_f32 v[4:5], v[32:33], v[6:7]
	v_pk_mul_f32 v[14:15], v[14:15], v[104:105] op_sel_hi:[1,0]
	v_sub_f32_e32 v4, v4, v5
	v_mul_f32_e32 v32, 0x3e38aa3b, v4
	v_pk_mul_f32 v[4:5], v[16:17], v[6:7]
	v_pk_mul_f32 v[14:15], v[14:15], v[116:117]
	v_add_f32_e32 v4, v4, v5
	v_mul_f32_e32 v6, 0x3e38aa3b, v4
	v_pk_mul_f32 v[4:5], v[72:73], v[14:15]
	v_pk_mul_f32 v[22:23], v[22:23], v[104:105] op_sel_hi:[1,0]
	v_sub_f32_e32 v4, v4, v5
	v_mul_f32_e32 v7, 0x3e38aa3b, v4
	v_pk_mul_f32 v[4:5], v[76:77], v[14:15]
	v_pk_mul_f32 v[22:23], v[22:23], v[150:151]
	v_add_f32_e32 v4, v4, v5
	v_mul_f32_e32 v14, 0x3e38aa3b, v4
	v_pk_mul_f32 v[4:5], v[18:19], v[22:23]
	v_pk_mul_f32 v[50:51], v[50:51], v[104:105] op_sel_hi:[1,0]
	v_sub_f32_e32 v4, v4, v5
	v_mul_f32_e32 v15, 0x3e38aa3b, v4
	v_pk_mul_f32 v[4:5], v[34:35], v[22:23]
	v_pk_mul_f32 v[50:51], v[50:51], v[112:113]
	v_add_f32_e32 v4, v4, v5
	v_mul_f32_e32 v16, 0x3e38aa3b, v4
	v_pk_mul_f32 v[4:5], v[86:87], v[50:51]
	v_pk_mul_f32 v[0:1], v[0:1], v[104:105] op_sel_hi:[1,0]
	v_sub_f32_e32 v4, v4, v5
	v_mul_f32_e32 v17, 0x3e38aa3b, v4
	v_pk_mul_f32 v[4:5], v[70:71], v[50:51]
	v_pk_mul_f32 v[0:1], v[0:1], v[102:103]
	v_add_f32_e32 v4, v4, v5
	v_pk_mul_f32 v[8:9], v[8:9], v[104:105] op_sel_hi:[1,0]
	v_mul_f32_e32 v18, 0x3e38aa3b, v4
	v_pk_mul_f32 v[4:5], v[36:37], v[0:1]
	v_pk_mul_f32 v[0:1], v[20:21], v[0:1]
	v_pk_mul_f32 v[8:9], v[8:9], v[90:91]
	v_add_f32_e32 v0, v0, v1
	v_sub_f32_e32 v4, v4, v5
	v_mul_f32_e32 v5, 0x3e38aa3b, v0
	v_pk_mul_f32 v[0:1], v[68:69], v[8:9]
	v_pk_mul_f32 v[58:59], v[58:59], v[104:105] op_sel_hi:[1,0]
	v_sub_f32_e32 v0, v0, v1
	v_mul_f32_e32 v19, 0x3e38aa3b, v0
	v_pk_mul_f32 v[0:1], v[92:93], v[8:9]
	v_pk_mul_f32 v[58:59], v[58:59], v[126:127]
	v_add_f32_e32 v0, v0, v1
	v_mul_f32_e32 v8, 0x3e38aa3b, v0
	v_pk_mul_f32 v[0:1], v[24:25], v[58:59]
	v_pk_mul_f32 v[48:49], v[48:49], v[104:105] op_sel_hi:[1,0]
	v_sub_f32_e32 v0, v0, v1
	v_mul_f32_e32 v9, 0x3e38aa3b, v0
	v_pk_mul_f32 v[0:1], v[38:39], v[58:59]
	v_pk_mul_f32 v[48:49], v[48:49], v[82:83]
	v_add_f32_e32 v0, v0, v1
	v_mul_f32_e32 v20, 0x3e38aa3b, v0
	v_pk_mul_f32 v[0:1], v[94:95], v[48:49]
	v_pk_mul_f32 v[2:3], v[2:3], v[104:105] op_sel_hi:[1,0]
	v_sub_f32_e32 v0, v0, v1
	v_mul_f32_e32 v21, 0x3e38aa3b, v0
	v_pk_mul_f32 v[0:1], v[66:67], v[48:49]
	v_pk_mul_f32 v[2:3], v[2:3], v[146:147]
	v_add_f32_e32 v0, v0, v1
	v_mul_f32_e32 v22, 0x3e38aa3b, v0
	v_pk_mul_f32 v[0:1], v[40:41], v[2:3]
	v_pk_mul_f32 v[10:11], v[10:11], v[104:105] op_sel_hi:[1,0]
	v_sub_f32_e32 v0, v0, v1
	v_mul_f32_e32 v23, 0x3e38aa3b, v0
	v_pk_mul_f32 v[0:1], v[26:27], v[2:3]
	global_load_dword v2, v199, s[0:1]
	v_pk_mul_f32 v[10:11], v[10:11], v[84:85]
	v_add_f32_e32 v0, v0, v1
	v_mul_f32_e32 v3, 0x3e38aa3b, v0
	v_pk_mul_f32 v[0:1], v[56:57], v[10:11]
	v_cmp_lt_i32_e32 vcc, v215, v209
	v_sub_f32_e32 v0, v0, v1
	v_mul_f32_e32 v24, 0x3e38aa3b, v0
	v_mov_b32_e32 v0, v57
	v_mov_b32_e32 v1, v56
	v_pk_mul_f32 v[0:1], v[0:1], v[10:11]
	v_mul_f32_e32 v4, 0x3e38aa3b, v4
	v_add_f32_e32 v0, v0, v1
	v_cndmask_b32_e32 v1, v207, v215, vcc
	v_mul_f32_e32 v10, 0x3e38aa3b, v0
	s_waitcnt vmcnt(2)
	v_and_b32_e32 v0, 0x7fffffff, v29
	v_lshlrev_b32_e32 v223, 2, v1
	ds_bpermute_b32 v0, v223, v0
	s_waitcnt vmcnt(1)
	v_and_b32_e32 v1, 0x7fffffff, v28
	ds_bpermute_b32 v1, v223, v1
	v_cmp_lt_i32_e32 vcc, v216, v209
	v_cvt_pk_bf16_f32 v146, v15, v4
	v_cvt_pk_bf16_f32 v147, v9, v23
	s_waitcnt lgkmcnt(1)
	v_max_f32_e32 v0, v0, v0
	v_max_f32_e64 v4, |v29|, |v29|
	v_cndmask_b32_e32 v9, v207, v216, vcc
	v_max_f32_e32 v0, v4, v0
	v_lshlrev_b32_e32 v224, 2, v9
	s_waitcnt lgkmcnt(0)
	v_max_f32_e32 v1, v1, v1
	v_max_f32_e64 v4, |v28|, |v28|
	ds_bpermute_b32 v9, v224, v0
	v_max_f32_e32 v1, v4, v1
	ds_bpermute_b32 v4, v224, v1
	v_cvt_pk_bf16_f32 v150, v16, v5
	v_cmp_lt_i32_e32 vcc, v217, v209
	s_waitcnt lgkmcnt(1)
	v_max_f32_e32 v5, v9, v9
	v_max_f32_e32 v0, v0, v5
	v_cndmask_b32_e32 v5, v207, v217, vcc
	s_waitcnt lgkmcnt(0)
	v_max_f32_e32 v4, v4, v4
	v_lshlrev_b32_e32 v5, 2, v5
	v_cvt_pk_bf16_f32 v149, v45, v6
	ds_bpermute_b32 v6, v5, v0
	v_max_f32_e32 v1, v1, v4
	ds_bpermute_b32 v4, v5, v1
	v_cvt_pk_bf16_f32 v151, v20, v3
	v_cmp_lt_i32_e32 vcc, v218, v209
	s_waitcnt lgkmcnt(1)
	v_max_f32_e32 v3, v6, v6
	v_max_f32_e32 v0, v0, v3
	s_waitcnt lgkmcnt(0)
	v_max_f32_e32 v3, v4, v4
	v_cndmask_b32_e32 v4, v207, v218, vcc
	v_lshlrev_b32_e32 v4, 2, v4
	ds_bpermute_b32 v5, v4, v0
	v_max_f32_e32 v1, v1, v3
	ds_bpermute_b32 v3, v4, v1
	v_cmp_lt_i32_e32 vcc, v219, v209
	s_mov_b32 s0, 0x3fb8aa3b
	s_waitcnt lgkmcnt(1)
	v_max_f32_e32 v4, v5, v5
	v_max_f32_e32 v0, v0, v4
	v_cndmask_b32_e32 v4, v207, v219, vcc
	s_waitcnt lgkmcnt(0)
	v_max_f32_e32 v3, v3, v3
	v_lshlrev_b32_e32 v4, 2, v4
	ds_bpermute_b32 v5, v4, v0
	v_max_f32_e32 v1, v1, v3
	ds_bpermute_b32 v3, v4, v1
	v_ashrrev_i32_e32 v200, 2, v96
	v_ashrrev_i32_e32 v201, 31, v200
	s_waitcnt lgkmcnt(1)
	v_max_f32_e32 v4, v5, v5
	v_max_f32_e32 v0, v0, v4
	s_waitcnt lgkmcnt(0)
	v_max_f32_e32 v3, v3, v3
	ds_bpermute_b32 v4, v221, v0
	v_max_f32_e32 v1, v1, v3
	ds_bpermute_b32 v3, v221, v1
	v_bfe_u32 v225, v96, 1, 1
	v_and_b32_e32 v226, 1, v96
	s_waitcnt lgkmcnt(1)
	v_max_f32_e32 v4, v4, v4
	v_max_f32_e32 v0, v0, v4
	s_waitcnt lgkmcnt(0)
	v_max_f32_e32 v3, v3, v3
	v_max_f32_e32 v1, v1, v3
	v_mul_f32_e32 v0, 0x41000000, v0
	v_mul_f32_e32 v0, v1, v0
	v_mul_f32_e32 v0, 0x3fb8aa3b, v0
	s_waitcnt vmcnt(0)
	v_mul_f32_e32 v235, 0x3fb8aa3b, v2
	v_fmamk_f32 v0, v0, 0x3f828f5c, v212
	v_max_f32_e32 v4, v0, v235
	v_fma_f32 v5, v2, s0, -v4
	s_add_u32 s0, s52, 0x10000
	s_addc_u32 s1, s53, 0
	v_lshl_add_u64 v[0:1], s[0:1], 0, v[200:201]
	v_mov_b64_e32 v[2:3], s[28:29]
	v_mad_u64_u32 v[2:3], s[0:1], v0, s25, v[2:3]
	v_mad_i32_i24 v3, v1, s25, v3
	s_lshl_b32 s8, s2, 7
	v_lshl_add_u64 v[0:1], v[2:3], 0, s[8:9]
	v_lshlrev_b32_e32 v198, 6, v225
	v_and_b32_e32 v6, 3, v96
	v_lshl_add_u64 v[2:3], v[0:1], 0, v[198:199]
	v_lshlrev_b32_e32 v198, 4, v226
	v_lshl_add_u64 v[2:3], v[2:3], 0, v[198:199]
	v_lshlrev_b32_e32 v198, 5, v6
	v_lshl_add_u64 v[0:1], v[0:1], 0, v[198:199]
	v_mov_b64_e32 v[88:89], v[176:177]
	v_mov_b64_e32 v[90:91], v[178:179]
	v_mov_b64_e32 v[92:93], v[180:181]
	v_mov_b64_e32 v[94:95], v[182:183]
	v_mov_b64_e32 v[80:81], v[184:185]
	v_mov_b64_e32 v[82:83], v[186:187]
	v_mov_b64_e32 v[84:85], v[188:189]
	v_mov_b64_e32 v[86:87], v[190:191]
	v_exp_f32_e32 v0, v5
	v_cmp_gt_f32_e32 vcc, s31, v4
	v_cmp_gt_u32_e64 s[0:1], 32, v98
	s_ashr_i32 s5, s4, 31
	v_cndmask_b32_e32 v0, 1.0, v0, vcc
	s_lshl_b32 s85, s7, 1
	v_cndmask_b32_e64 v227, 0, v0, s[0:1]
	s_add_i32 s84, s72, -2
	s_lshl_b64 s[0:1], s[4:5], 12
	s_or_b32 s86, s85, 1
	v_lshlrev_b32_e32 v1, 4, v96
	v_lshl_add_u32 v0, v225, 13, 0
	s_add_u32 s52, s52, 0x10080
	v_and_b32_e32 v1, 0xc0, v1
	v_lshlrev_b32_e32 v2, 1, v96
	v_sub_f32_e32 v60, v60, v61
	v_mul_f32_e32 v30, 0x3e38aa3b, v30
	v_cvt_pk_bf16_f32 v154, v17, v19
	v_cvt_pk_bf16_f32 v155, v21, v24
	v_cvt_pk_bf16_f32 v157, v47, v14
	v_cvt_pk_bf16_f32 v158, v18, v8
	v_cvt_pk_bf16_f32 v159, v22, v10
	v_lshlrev_b32_e32 v16, 5, v225
	v_lshlrev_b32_e32 v18, 3, v226
	v_lshlrev_b32_e32 v20, 4, v6
	v_lshl_add_u32 v17, v226, 11, v0
	v_lshlrev_b32_e32 v19, 4, v200
	v_lshl_add_u32 v21, v200, 6, v0
	v_lshlrev_b32_e32 v22, 5, v226
	v_lshlrev_b32_e32 v0, 4, v222
	s_addc_u32 s53, s53, 0
	v_lshl_or_b32 v1, v97, 8, v1
	v_and_b32_e32 v2, 32, v2
	v_lshlrev_b32_e32 v3, 3, v6
	v_mov_b32_e32 v14, v199
	v_mov_b32_e32 v15, v199
	v_mul_f32_e32 v60, 0x3e38aa3b, v60
	v_cvt_pk_bf16_f32 v144, v60, v30
	v_cvt_pk_bf16_f32 v145, v13, v32
	v_cvt_pk_bf16_f32 v148, v42, v31
	v_cvt_pk_bf16_f32 v152, v43, v44
	v_cvt_pk_bf16_f32 v153, v46, v7
	v_cvt_pk_bf16_f32 v156, v54, v12
	v_cmp_ngt_f32_e64 s[2:3], s31, v4
	v_cndmask_b32_e64 v48, 0, -v4, vcc
	v_cmp_gt_u32_e64 s[4:5], 2, v6
	v_or_b32_e32 v229, s6, v222
	s_add_u32 s54, s28, s8
	v_or3_b32 v231, v1, v2, v3
	v_lshl_or_b32 v232, v97, 11, v0
	v_mov_b32_e32 v0, v199
	v_mov_b32_e32 v1, v199
	v_mov_b32_e32 v2, v199
	v_mov_b32_e32 v3, v199
	v_mov_b32_e32 v4, v199
	v_mov_b32_e32 v5, v199
	v_mov_b32_e32 v6, v199
	v_mov_b32_e32 v7, v199
	v_mov_b32_e32 v8, v199
	v_mov_b32_e32 v9, v199
	v_mov_b32_e32 v10, v199
	v_mov_b32_e32 v11, v199
	v_mov_b32_e32 v12, v199
	v_mov_b32_e32 v13, v199
	v_lshlrev_b32_e32 v198, 1, v16
	v_lshlrev_b32_e32 v202, 1, v18
	v_lshlrev_b32_e32 v204, 1, v20
	v_add_u32_e32 v233, v17, v19
	v_add_u32_e32 v234, v21, v22
	v_mov_b64_e32 v[30:31], v[14:15]
	v_mov_b64_e32 v[46:47], v[14:15]
	v_mov_b64_e32 v[78:79], v[14:15]
	s_mov_b32 s73, 0
	v_lshlrev_b32_e32 v228, 2, v97
	v_mov_b32_e32 v49, v48
	v_mov_b32_e32 v50, v48
	v_mov_b32_e32 v51, v48
	v_mov_b32_e32 v52, v48
	v_mov_b32_e32 v53, v48
	v_mov_b32_e32 v54, v48
	v_mov_b32_e32 v55, v48
	v_mov_b32_e32 v56, v48
	v_mov_b32_e32 v57, v48
	v_mov_b32_e32 v58, v48
	v_mov_b32_e32 v59, v48
	v_mov_b32_e32 v60, v48
	v_mov_b32_e32 v61, v48
	v_mov_b32_e32 v62, v48
	v_mov_b32_e32 v63, v48
	v_or_b32_e32 v230, 32, v229
	s_addc_u32 s55, s29, 0
	v_mov_b32_e32 v113, v235
	v_mov_b32_e32 v112, v227
	v_mov_b64_e32 v[28:29], v[12:13]
	v_mov_b64_e32 v[26:27], v[10:11]
	v_mov_b64_e32 v[24:25], v[8:9]
	v_mov_b64_e32 v[22:23], v[6:7]
	v_mov_b64_e32 v[20:21], v[4:5]
	v_mov_b64_e32 v[18:19], v[2:3]
	v_mov_b64_e32 v[16:17], v[0:1]
	v_mov_b64_e32 v[44:45], v[12:13]
	v_mov_b64_e32 v[42:43], v[10:11]
	v_mov_b64_e32 v[40:41], v[8:9]
	v_mov_b64_e32 v[38:39], v[6:7]
	v_mov_b64_e32 v[36:37], v[4:5]
	v_mov_b64_e32 v[34:35], v[2:3]
	v_mov_b64_e32 v[32:33], v[0:1]
	v_mov_b64_e32 v[76:77], v[12:13]
	v_mov_b64_e32 v[74:75], v[10:11]
	v_mov_b64_e32 v[72:73], v[8:9]
	v_mov_b64_e32 v[70:71], v[6:7]
	v_mov_b64_e32 v[68:69], v[4:5]
	v_mov_b64_e32 v[66:67], v[2:3]
	v_mov_b64_e32 v[64:65], v[0:1]
	s_mov_b64 s[6:7], -1
	s_cmp_lt_u32 s73, 2
	s_mov_b32 s8, 0
	s_cbranch_scc1 .LBB0_408
